# od-out RESID epilogue rewritten: 3-row-deep pipelined x loads with counted vmcnt, scalar row pointers, tile-uniform x/ctx select (on top of SQRELU change)
# baseline (speedup 1.0000x reference)
; template <int EPI>
; DI float epi8(const Epi& e, int r, int c, f32x4 v0, f32x4 v1, float rinv, float4 s0, float4 s1, float4 t0, float4 t1) {
;     ...
;   } else if constexpr (EPI == EPI_RESID) {
;     const float* src; float* dst;
;     if (r < NX) { src = e.xi + (size_t)r * 1024 + c; dst = e.xo + (size_t)r * 1024 + c; }
;     else { int rc = r - NX; src = e.ci + (size_t)rc * 1024 + c; dst = e.co + (size_t)rc * 1024 + c; }
;     float4 x0 = *(const float4*)src, x1 = *(const float4*)(src + 4);
;     float4 o0, o1;
;     o0.x = x0.x + s0.x * v0[0]; o0.y = x0.y + s0.y * v0[1]; o0.z = x0.z + s0.z * v0[2]; o0.w = x0.w + s0.w * v0[3];
;     o1.x = x1.x + s1.x * v1[0]; o1.y = x1.y + s1.y * v1[1]; o1.z = x1.z + s1.z * v1[2]; o1.w = x1.w + s1.w * v1[3];
;     *(float4*)dst = o0; *(float4*)(dst + 4) = o1;
;     if (e.hout) {
;       uint4 h;
;       h.x = pack2(o0.x * t0.x, o0.y * t0.y); h.y = pack2(o0.z * t0.z, o0.w * t0.w);
;       h.z = pack2(o1.x * t1.x, o1.y * t1.y); h.w = pack2(o1.z * t1.z, o1.w * t1.w);
;       *(uint4*)(e.hout + (size_t)r * 1024 + c) = h;
;       return (o0.x * o0.x + o0.y * o0.y) + (o0.z * o0.z + o0.w * o0.w) + (o1.x * o1.x + o1.y * o1.y) + (o1.z * o1.z + o1.w * o1.w);
;     }
; template <int EPI>
; DI void gemm_phase(const u16* __restrict__ A, int lda, const u16* __restrict__ Bt, int ldb,
;                    int M, int N, int K, const Epi& e, unsigned char* shmraw, int wv, int slot) {
;     ...
;         const int c = bcol + bj * HALF + wc2 * 32 + fq2 * 8;
;         cs[bj][0] = cs[bj][1] = ct[bj][0] = ct[bj][1] = make_float4(0.f, 0.f, 0.f, 0.f);
;         if constexpr (EPI == EPI_FT || EPI == EPI_VT) {
;           if (e.stats) { f32x4 ra = row_rinv4(e.stats, c), rb = row_rinv4(e.stats, c + 4); cs[bj][0] = make_float4(ra[0], ra[1], ra[2], ra[3]); cs[bj][1] = make_float4(rb[0], rb[1], rb[2], rb[3]); }
;         } else if constexpr (EPI == EPI_STORE || EPI == EPI_SQRELU) {
;           if (e.stats) { const float* sp = e.shw + (size_t)mrow_t * 4096 + c; cs[bj][0] = *(const float4*)sp; cs[bj][1] = *(const float4*)(sp + 4); }
;         } else if constexpr (EPI == EPI_RESID) {
;           const float* gp = e.gate + (size_t)mrow_t * 6144 + c; cs[bj][0] = *(const float4*)gp; cs[bj][1] = *(const float4*)(gp + 4);
;           if (e.hout) {
;             const float* np = e.ngain + c; const float* scp = e.nscale + (size_t)mrow_t * 6144 + c;
.LBB0_655:
	v_mbcnt_lo_u32_b32 v210, -1, 0
	v_mbcnt_hi_u32_b32 v210, -1, v210
	v_readlane_b32 s20, v255, 36
	v_readlane_b32 s21, v255, 35
	v_readlane_b32 s10, v255, 38
	v_readlane_b32 s11, v255, 37
	s_sub_u32 s10, s10, 0x10000000
	s_subb_u32 s11, s11, 0
	s_cmp_lt_i32 s18, 0x10000
	s_cselect_b32 s20, s20, s10
	s_cselect_b32 s21, s21, s11
	v_readlane_b32 s22, v255, 23
	v_readlane_b32 s23, v255, 24
	s_mov_b32 s10, s87
	s_mov_b32 s11, s16
	s_sub_u32 s10, s10, 0x10000000
	s_subb_u32 s11, s11, 0
	s_cmp_lt_i32 s18, 0x10000
	s_cselect_b32 s22, s22, s10
	s_cselect_b32 s23, s23, s11
	s_mov_b32 s26, s82
	s_mov_b32 s27, s83
	v_add_u32_e32 v154, s53, v210
	v_bfe_u32 v211, v154, 6, 2
	v_lshrrev_b32_e32 v0, 1, v210
	s_lshl_b32 s1, s70, 8
	v_lshlrev_b32_e32 v218, 5, v211
	v_and_b32_e32 v0, 24, v0
	v_or3_b32 v218, v218, v0, s1
	v_and_b32_e32 v155, 15, v210
	v_ashrrev_i32_e32 v209, 8, v154
	v_or_b32_e32 v0, s18, v155
	v_lshl_add_u32 v0, v209, 6, v0
	v_lshlrev_b32_e32 v216, 12, v0
	v_lshl_add_u32 v216, v218, 2, v216
	v_lshlrev_b32_e32 v218, 2, v218
	v_lshrrev_b32_e32 v217, 1, v216
	s_min_i32 s49, s71, 0x100
	s_ashr_i32 s49, s49, 3
	s_mul_i32 s49, s49, 0x6000
	s_add_u32 s10, s31, s49
	s_addc_u32 s11, s43, 0
	global_load_dwordx4 v[30:33], v218, s[10:11]
	global_load_dwordx4 v[26:29], v218, s[10:11] offset:16
	global_load_dwordx4 v[22:25], v218, s[10:11] offset:512
	global_load_dwordx4 v[18:21], v218, s[10:11] offset:528
	global_load_dwordx4 v[156:159], v218, s[8:9]
	global_load_dwordx4 v[160:163], v218, s[8:9] offset:16
	global_load_dwordx4 v[164:167], v218, s[8:9] offset:512
	global_load_dwordx4 v[168:171], v218, s[8:9] offset:528
	s_add_u32 s10, s96, s49
	s_addc_u32 s11, s97, 0
	global_load_dwordx4 v[242:245], v218, s[10:11]
	global_load_dwordx4 v[246:249], v218, s[10:11] offset:16
	global_load_dwordx4 v[220:223], v218, s[10:11] offset:512
	global_load_dwordx4 v[224:227], v218, s[10:11] offset:528
	global_load_dwordx4 v[172:175], v216, s[20:21]
	global_load_dwordx4 v[176:179], v216, s[20:21] offset:16
	global_load_dwordx4 v[180:183], v216, s[20:21] offset:512
	global_load_dwordx4 v[184:187], v216, s[20:21] offset:528
	s_add_u32 s20, s20, 0x10000
	s_addc_u32 s21, s21, 0
	global_load_dwordx4 v[188:191], v216, s[20:21]
	global_load_dwordx4 v[230:233], v216, s[20:21] offset:16
	global_load_dwordx4 v[234:237], v216, s[20:21] offset:512
	global_load_dwordx4 v[238:241], v216, s[20:21] offset:528
	s_add_u32 s20, s20, 0x10000
	s_addc_u32 s21, s21, 0
	s_waitcnt vmcnt(8)
	v_pk_add_f32 v[242:243], v[242:243], 1.0 op_sel_hi:[1,0]
	v_pk_add_f32 v[244:245], v[244:245], 1.0 op_sel_hi:[1,0]
	v_pk_add_f32 v[246:247], v[246:247], 1.0 op_sel_hi:[1,0]
	v_pk_add_f32 v[248:249], v[248:249], 1.0 op_sel_hi:[1,0]
	v_pk_add_f32 v[220:221], v[220:221], 1.0 op_sel_hi:[1,0]
	v_pk_add_f32 v[222:223], v[222:223], 1.0 op_sel_hi:[1,0]
	v_pk_add_f32 v[224:225], v[224:225], 1.0 op_sel_hi:[1,0]
	v_pk_add_f32 v[226:227], v[226:227], 1.0 op_sel_hi:[1,0]
	v_pk_mul_f32 v[156:157], v[156:157], v[242:243]
	v_pk_mul_f32 v[158:159], v[158:159], v[244:245]
	v_pk_mul_f32 v[160:161], v[160:161], v[246:247]
	v_pk_mul_f32 v[162:163], v[162:163], v[248:249]
	v_pk_mul_f32 v[164:165], v[164:165], v[220:221]
	v_pk_mul_f32 v[166:167], v[166:167], v[222:223]
	v_pk_mul_f32 v[168:169], v[168:169], v[224:225]
	v_pk_mul_f32 v[170:171], v[170:171], v[226:227]
	global_load_dwordx4 v[242:245], v216, s[20:21]
	global_load_dwordx4 v[246:249], v216, s[20:21] offset:16
	global_load_dwordx4 v[220:223], v216, s[20:21] offset:512
	global_load_dwordx4 v[224:227], v216, s[20:21] offset:528
	s_add_u32 s20, s20, 0x10000
	s_addc_u32 s21, s21, 0
	s_waitcnt vmcnt(8)
	v_pk_fma_f32 v[138:139], v[138:139], v[30:31], v[172:173]
	v_pk_fma_f32 v[140:141], v[140:141], v[32:33], v[174:175]
	v_pk_fma_f32 v[146:147], v[146:147], v[26:27], v[176:177]
	v_pk_fma_f32 v[148:149], v[148:149], v[28:29], v[178:179]
	v_pk_fma_f32 v[54:55], v[54:55], v[22:23], v[180:181]
	v_pk_fma_f32 v[56:57], v[56:57], v[24:25], v[182:183]
	v_pk_fma_f32 v[134:135], v[134:135], v[18:19], v[184:185]
	v_pk_fma_f32 v[136:137], v[136:137], v[20:21], v[186:187]
	global_store_dwordx4 v216, v[138:141], s[22:23]
	global_store_dwordx4 v216, v[146:149], s[22:23] offset:16
	v_pk_mul_f32 v[142:143], v[156:157], v[138:139]
	v_pk_mul_f32 v[144:145], v[158:159], v[140:141]
	v_pk_mul_f32 v[172:173], v[160:161], v[146:147]
	v_pk_mul_f32 v[174:175], v[162:163], v[148:149]
	v_cvt_pk_bf16_f32 v142, v142, v143
	v_cvt_pk_bf16_f32 v143, v144, v145
	v_cvt_pk_bf16_f32 v144, v172, v173
	v_cvt_pk_bf16_f32 v145, v174, v175
	global_store_dwordx4 v217, v[142:145], s[26:27]
	global_store_dwordx4 v216, v[54:57], s[22:23] offset:512
	global_store_dwordx4 v216, v[134:137], s[22:23] offset:528
	v_pk_mul_f32 v[212:213], v[164:165], v[54:55]
	v_pk_mul_f32 v[214:215], v[166:167], v[56:57]
	v_pk_mul_f32 v[172:173], v[168:169], v[134:135]
	v_pk_mul_f32 v[174:175], v[170:171], v[136:137]
	v_cvt_pk_bf16_f32 v212, v212, v213
	v_cvt_pk_bf16_f32 v213, v214, v215
	v_cvt_pk_bf16_f32 v214, v172, v173
	v_cvt_pk_bf16_f32 v215, v174, v175
	global_store_dwordx4 v217, v[212:215], s[26:27] offset:256
	v_pk_mul_f32 v[228:229], v[138:139], v[138:139]
	v_pk_fma_f32 v[228:229], v[140:141], v[140:141], v[228:229]
	v_pk_fma_f32 v[228:229], v[146:147], v[146:147], v[228:229]
	v_pk_fma_f32 v[228:229], v[148:149], v[148:149], v[228:229]
	v_pk_fma_f32 v[228:229], v[54:55], v[54:55], v[228:229]
	v_pk_fma_f32 v[228:229], v[56:57], v[56:57], v[228:229]
	v_pk_fma_f32 v[228:229], v[134:135], v[134:135], v[228:229]
	v_pk_fma_f32 v[228:229], v[136:137], v[136:137], v[228:229]
	global_load_dwordx4 v[172:175], v216, s[20:21]
	global_load_dwordx4 v[176:179], v216, s[20:21] offset:16
	global_load_dwordx4 v[180:183], v216, s[20:21] offset:512
	global_load_dwordx4 v[184:187], v216, s[20:21] offset:528
	s_add_u32 s20, s20, 0x50000
	s_addc_u32 s21, s21, 0
	v_add_f32_e32 v138, v228, v229
	s_add_u32 s22, s22, 0x10000
	s_addc_u32 s23, s23, 0
	s_add_u32 s26, s26, 0x8000
	s_addc_u32 s27, s27, 0
	s_waitcnt vmcnt(14)
; template <int EPI>
; DI float epi8(const Epi& e, int r, int c, f32x4 v0, f32x4 v1, float rinv, float4 s0, float4 s1, float4 t0, float4 t1) {
;     ...
;   } else if constexpr (EPI == EPI_RESID) {
;     const float* src; float* dst;
;     if (r < NX) { src = e.xi + (size_t)r * 1024 + c; dst = e.xo + (size_t)r * 1024 + c; }
;     else { int rc = r - NX; src = e.ci + (size_t)rc * 1024 + c; dst = e.co + (size_t)rc * 1024 + c; }
;     float4 x0 = *(const float4*)src, x1 = *(const float4*)(src + 4);
;     float4 o0, o1;
;     o0.x = x0.x + s0.x * v0[0]; o0.y = x0.y + s0.y * v0[1]; o0.z = x0.z + s0.z * v0[2]; o0.w = x0.w + s0.w * v0[3];
;     o1.x = x1.x + s1.x * v1[0]; o1.y = x1.y + s1.y * v1[1]; o1.z = x1.z + s1.z * v1[2]; o1.w = x1.w + s1.w * v1[3];
;     *(float4*)dst = o0; *(float4*)(dst + 4) = o1;
;     if (e.hout) {
;       uint4 h;
;       h.x = pack2(o0.x * t0.x, o0.y * t0.y); h.y = pack2(o0.z * t0.z, o0.w * t0.w);
;       h.z = pack2(o1.x * t1.x, o1.y * t1.y); h.w = pack2(o1.z * t1.z, o1.w * t1.w);
;       *(uint4*)(e.hout + (size_t)r * 1024 + c) = h;
;       return (o0.x * o0.x + o0.y * o0.y) + (o0.z * o0.z + o0.w * o0.w) + (o1.x * o1.x + o1.y * o1.y) + (o1.z * o1.z + o1.w * o1.w);
;     }
; template <int EPI>
; DI void gemm_phase(const u16* __restrict__ A, int lda, const u16* __restrict__ Bt, int ldb,
;                    int M, int N, int K, const Epi& e, unsigned char* shmraw, int wv, int slot) {
;     ...
;       float rowss[2][4];
; #pragma unroll
;       for (int ai = 0; ai < 2; ++ai)
; #pragma unroll
;         for (int m = 0; m < 4; ++m) {
;           const int row = brow + ai * HALF + wr2 * 64 + m * 16 + fr2;
;           float rinv = 1.f;
;           if constexpr (EPI == EPI_STORE || EPI == EPI_SQRELU) { if (e.stats) rinv = row_rinv(e.stats, row); }
;           if constexpr (EPI == EPI_FT || EPI == EPI_VT) { rinv = e.stats ? e.shw[(size_t)mrow_t * 4096 + row] : 0.f; }
;           float ss = 0.f;
; #pragma unroll
;           for (int bj = 0; bj < 2; ++bj)
;             ss += epi8<EPI>(e, row, bcol + bj * HALF + wc2 * 32 + fq2 * 8, acc[ai][bj][m][0], acc[ai][bj][m][1], rinv, cs[bj][0], cs[bj][1], ct[bj][0], ct[bj][1]);
;           rowss[ai][m] = ss;
;         }
	v_pk_fma_f32 v[54:55], v[50:51], v[30:31], v[188:189]
	v_pk_fma_f32 v[56:57], v[52:53], v[32:33], v[190:191]
	v_pk_fma_f32 v[50:51], v[70:71], v[26:27], v[230:231]
	v_pk_fma_f32 v[52:53], v[72:73], v[28:29], v[232:233]
	v_pk_fma_f32 v[70:71], v[66:67], v[22:23], v[234:235]
	v_pk_fma_f32 v[72:73], v[68:69], v[24:25], v[236:237]
	v_pk_fma_f32 v[66:67], v[86:87], v[18:19], v[238:239]
	v_pk_fma_f32 v[68:69], v[88:89], v[20:21], v[240:241]
	global_store_dwordx4 v216, v[54:57], s[22:23]
	global_store_dwordx4 v216, v[50:53], s[22:23] offset:16
	v_pk_mul_f32 v[142:143], v[156:157], v[54:55]
	v_pk_mul_f32 v[144:145], v[158:159], v[56:57]
	v_pk_mul_f32 v[188:189], v[160:161], v[50:51]
	v_pk_mul_f32 v[190:191], v[162:163], v[52:53]
	v_cvt_pk_bf16_f32 v142, v142, v143
	v_cvt_pk_bf16_f32 v143, v144, v145
	v_cvt_pk_bf16_f32 v144, v188, v189
	v_cvt_pk_bf16_f32 v145, v190, v191
	global_store_dwordx4 v217, v[142:145], s[26:27]
	global_store_dwordx4 v216, v[70:73], s[22:23] offset:512
	global_store_dwordx4 v216, v[66:69], s[22:23] offset:528
	v_pk_mul_f32 v[212:213], v[164:165], v[70:71]
	v_pk_mul_f32 v[214:215], v[166:167], v[72:73]
	v_pk_mul_f32 v[188:189], v[168:169], v[66:67]
	v_pk_mul_f32 v[190:191], v[170:171], v[68:69]
	v_cvt_pk_bf16_f32 v212, v212, v213
	v_cvt_pk_bf16_f32 v213, v214, v215
	v_cvt_pk_bf16_f32 v214, v188, v189
	v_cvt_pk_bf16_f32 v215, v190, v191
	global_store_dwordx4 v217, v[212:215], s[26:27] offset:256
	global_load_dwordx4 v[188:191], v216, s[20:21]
	global_load_dwordx4 v[230:233], v216, s[20:21] offset:16
	global_load_dwordx4 v[234:237], v216, s[20:21] offset:512
	global_load_dwordx4 v[238:241], v216, s[20:21] offset:528
	s_add_u32 s20, s20, 0x10000
	s_addc_u32 s21, s21, 0
	s_add_u32 s22, s22, 0x10000
	s_addc_u32 s23, s23, 0
	s_add_u32 s26, s26, 0x8000
	s_addc_u32 s27, s27, 0
	s_waitcnt vmcnt(20)
	v_pk_fma_f32 v[86:87], v[82:83], v[30:31], v[242:243]
	v_pk_fma_f32 v[88:89], v[84:85], v[32:33], v[244:245]
	v_pk_fma_f32 v[82:83], v[102:103], v[26:27], v[246:247]
	v_pk_fma_f32 v[84:85], v[104:105], v[28:29], v[248:249]
	v_pk_fma_f32 v[102:103], v[98:99], v[22:23], v[220:221]
	v_pk_fma_f32 v[104:105], v[100:101], v[24:25], v[222:223]
	v_pk_fma_f32 v[98:99], v[118:119], v[18:19], v[224:225]
	v_pk_fma_f32 v[100:101], v[120:121], v[20:21], v[226:227]
	global_store_dwordx4 v216, v[86:89], s[22:23]
	global_store_dwordx4 v216, v[82:85], s[22:23] offset:16
	v_pk_mul_f32 v[142:143], v[156:157], v[86:87]
	v_pk_mul_f32 v[144:145], v[158:159], v[88:89]
	v_pk_mul_f32 v[242:243], v[160:161], v[82:83]
	v_pk_mul_f32 v[244:245], v[162:163], v[84:85]
	v_cvt_pk_bf16_f32 v142, v142, v143
	v_cvt_pk_bf16_f32 v143, v144, v145
	v_cvt_pk_bf16_f32 v144, v242, v243
	v_cvt_pk_bf16_f32 v145, v244, v245
	global_store_dwordx4 v217, v[142:145], s[26:27]
	global_store_dwordx4 v216, v[102:105], s[22:23] offset:512
	global_store_dwordx4 v216, v[98:101], s[22:23] offset:528
	v_pk_mul_f32 v[212:213], v[164:165], v[102:103]
	v_pk_mul_f32 v[214:215], v[166:167], v[104:105]
	v_pk_mul_f32 v[242:243], v[168:169], v[98:99]
	v_pk_mul_f32 v[244:245], v[170:171], v[100:101]
	v_cvt_pk_bf16_f32 v212, v212, v213
	v_cvt_pk_bf16_f32 v213, v214, v215
	v_cvt_pk_bf16_f32 v214, v242, v243
	v_cvt_pk_bf16_f32 v215, v244, v245
	global_store_dwordx4 v217, v[212:215], s[26:27] offset:256
	global_load_dwordx4 v[242:245], v216, s[20:21]
	global_load_dwordx4 v[246:249], v216, s[20:21] offset:16
	global_load_dwordx4 v[220:223], v216, s[20:21] offset:512
	global_load_dwordx4 v[224:227], v216, s[20:21] offset:528
	s_add_u32 s20, s20, 0x10000
	s_addc_u32 s21, s21, 0
	s_add_u32 s22, s22, 0x10000
	s_addc_u32 s23, s23, 0
	s_add_u32 s26, s26, 0x8000
	s_addc_u32 s27, s27, 0
	s_waitcnt vmcnt(20)
	v_pk_fma_f32 v[118:119], v[114:115], v[30:31], v[172:173]
	v_pk_fma_f32 v[120:121], v[116:117], v[32:33], v[174:175]
	v_pk_fma_f32 v[114:115], v[130:131], v[26:27], v[176:177]
	v_pk_fma_f32 v[116:117], v[132:133], v[28:29], v[178:179]
	v_pk_fma_f32 v[130:131], v[122:123], v[22:23], v[180:181]
	v_pk_fma_f32 v[132:133], v[124:125], v[24:25], v[182:183]
	v_pk_fma_f32 v[122:123], v[126:127], v[18:19], v[184:185]
	v_pk_fma_f32 v[124:125], v[128:129], v[20:21], v[186:187]
	global_store_dwordx4 v216, v[118:121], s[22:23]
	global_store_dwordx4 v216, v[114:117], s[22:23] offset:16
	v_pk_mul_f32 v[142:143], v[156:157], v[118:119]
	v_pk_mul_f32 v[144:145], v[158:159], v[120:121]
	v_pk_mul_f32 v[172:173], v[160:161], v[114:115]
	v_pk_mul_f32 v[174:175], v[162:163], v[116:117]
	v_cvt_pk_bf16_f32 v142, v142, v143
	v_cvt_pk_bf16_f32 v143, v144, v145
	v_cvt_pk_bf16_f32 v144, v172, v173
	v_cvt_pk_bf16_f32 v145, v174, v175
	global_store_dwordx4 v217, v[142:145], s[26:27]
	global_store_dwordx4 v216, v[130:133], s[22:23] offset:512
	global_store_dwordx4 v216, v[122:125], s[22:23] offset:528
	v_pk_mul_f32 v[212:213], v[164:165], v[130:131]
	v_pk_mul_f32 v[214:215], v[166:167], v[132:133]
	v_pk_mul_f32 v[172:173], v[168:169], v[122:123]
	v_pk_mul_f32 v[174:175], v[170:171], v[124:125]
	v_cvt_pk_bf16_f32 v212, v212, v213
	v_cvt_pk_bf16_f32 v213, v214, v215
	v_cvt_pk_bf16_f32 v214, v172, v173
	v_cvt_pk_bf16_f32 v215, v174, v175
	global_store_dwordx4 v217, v[212:215], s[26:27] offset:256
	global_load_dwordx4 v[172:175], v216, s[20:21]
	global_load_dwordx4 v[176:179], v216, s[20:21] offset:16
	global_load_dwordx4 v[180:183], v216, s[20:21] offset:512
	global_load_dwordx4 v[184:187], v216, s[20:21] offset:528
	s_add_u32 s20, s20, 0x10000
	s_addc_u32 s21, s21, 0
	s_add_u32 s22, s22, 0x50000
	s_addc_u32 s23, s23, 0
	s_add_u32 s26, s26, 0x28000
	s_addc_u32 s27, s27, 0
	s_waitcnt vmcnt(20)
; DI float shx(float v, int o, int lane) { return __int_as_float(__builtin_amdgcn_ds_bpermute((lane ^ o) << 2, __float_as_int(v))); }
; template <int EPI>
; DI float epi8(const Epi& e, int r, int c, f32x4 v0, f32x4 v1, float rinv, float4 s0, float4 s1, float4 t0, float4 t1) {
;     ...
;   } else if constexpr (EPI == EPI_RESID) {
;     const float* src; float* dst;
;     if (r < NX) { src = e.xi + (size_t)r * 1024 + c; dst = e.xo + (size_t)r * 1024 + c; }
;     else { int rc = r - NX; src = e.ci + (size_t)rc * 1024 + c; dst = e.co + (size_t)rc * 1024 + c; }
;     float4 x0 = *(const float4*)src, x1 = *(const float4*)(src + 4);
;     float4 o0, o1;
;     o0.x = x0.x + s0.x * v0[0]; o0.y = x0.y + s0.y * v0[1]; o0.z = x0.z + s0.z * v0[2]; o0.w = x0.w + s0.w * v0[3];
;     o1.x = x1.x + s1.x * v1[0]; o1.y = x1.y + s1.y * v1[1]; o1.z = x1.z + s1.z * v1[2]; o1.w = x1.w + s1.w * v1[3];
;     *(float4*)dst = o0; *(float4*)(dst + 4) = o1;
;     if (e.hout) {
;       uint4 h;
;       h.x = pack2(o0.x * t0.x, o0.y * t0.y); h.y = pack2(o0.z * t0.z, o0.w * t0.w);
;       h.z = pack2(o1.x * t1.x, o1.y * t1.y); h.w = pack2(o1.z * t1.z, o1.w * t1.w);
;       *(uint4*)(e.hout + (size_t)r * 1024 + c) = h;
;       return (o0.x * o0.x + o0.y * o0.y) + (o0.z * o0.z + o0.w * o0.w) + (o1.x * o1.x + o1.y * o1.y) + (o1.z * o1.z + o1.w * o1.w);
;     }
; template <int EPI>
; DI void gemm_phase(const u16* __restrict__ A, int lda, const u16* __restrict__ Bt, int ldb,
;                    int M, int N, int K, const Epi& e, unsigned char* shmraw, int wv, int slot) {
;     ...
;       if constexpr (EPI == EPI_RESID) {
;         if (e.hout) {
;           float* red = (float*)SA(1, 1);
; #pragma unroll
;           for (int ai = 0; ai < 2; ++ai)
; #pragma unroll
;             for (int m = 0; m < 4; ++m) {
;               float v = rowss[ai][m];
;               v += shx(v, 16, lane2); v += shx(v, 32, lane2);
;               if (fq2 == 0) red[(ai * HALF + wr2 * 64 + m * 16 + fr2) * 4 + wc2] = v;
;             }
	v_pk_fma_f32 v[126:127], v[106:107], v[30:31], v[188:189]
	v_pk_fma_f32 v[128:129], v[108:109], v[32:33], v[190:191]
	v_pk_fma_f32 v[106:107], v[110:111], v[26:27], v[230:231]
	v_pk_fma_f32 v[108:109], v[112:113], v[28:29], v[232:233]
	v_pk_fma_f32 v[110:111], v[90:91], v[22:23], v[234:235]
	v_pk_fma_f32 v[112:113], v[92:93], v[24:25], v[236:237]
	v_pk_fma_f32 v[90:91], v[94:95], v[18:19], v[238:239]
	v_pk_fma_f32 v[92:93], v[96:97], v[20:21], v[240:241]
	global_store_dwordx4 v216, v[126:129], s[22:23]
	global_store_dwordx4 v216, v[106:109], s[22:23] offset:16
	v_pk_mul_f32 v[142:143], v[156:157], v[126:127]
	v_pk_mul_f32 v[144:145], v[158:159], v[128:129]
	v_pk_mul_f32 v[188:189], v[160:161], v[106:107]
	v_pk_mul_f32 v[190:191], v[162:163], v[108:109]
	v_cvt_pk_bf16_f32 v142, v142, v143
	v_cvt_pk_bf16_f32 v143, v144, v145
	v_cvt_pk_bf16_f32 v144, v188, v189
	v_cvt_pk_bf16_f32 v145, v190, v191
	global_store_dwordx4 v217, v[142:145], s[26:27]
	global_store_dwordx4 v216, v[110:113], s[22:23] offset:512
	global_store_dwordx4 v216, v[90:93], s[22:23] offset:528
	v_pk_mul_f32 v[212:213], v[164:165], v[110:111]
	v_pk_mul_f32 v[214:215], v[166:167], v[112:113]
	v_pk_mul_f32 v[188:189], v[168:169], v[90:91]
	v_pk_mul_f32 v[190:191], v[170:171], v[92:93]
	v_cvt_pk_bf16_f32 v212, v212, v213
	v_cvt_pk_bf16_f32 v213, v214, v215
	v_cvt_pk_bf16_f32 v214, v188, v189
	v_cvt_pk_bf16_f32 v215, v190, v191
	global_store_dwordx4 v217, v[212:215], s[26:27] offset:256
	global_load_dwordx4 v[188:191], v216, s[20:21]
	global_load_dwordx4 v[230:233], v216, s[20:21] offset:16
	global_load_dwordx4 v[234:237], v216, s[20:21] offset:512
	global_load_dwordx4 v[238:241], v216, s[20:21] offset:528
	s_add_u32 s22, s22, 0x10000
	s_addc_u32 s23, s23, 0
	s_add_u32 s26, s26, 0x8000
	s_addc_u32 s27, s27, 0
	s_waitcnt vmcnt(20)
	v_pk_fma_f32 v[94:95], v[74:75], v[30:31], v[242:243]
	v_pk_fma_f32 v[96:97], v[76:77], v[32:33], v[244:245]
	v_pk_fma_f32 v[74:75], v[78:79], v[26:27], v[246:247]
	v_pk_fma_f32 v[76:77], v[80:81], v[28:29], v[248:249]
	v_pk_fma_f32 v[78:79], v[58:59], v[22:23], v[220:221]
	v_pk_fma_f32 v[80:81], v[60:61], v[24:25], v[222:223]
	v_pk_fma_f32 v[58:59], v[62:63], v[18:19], v[224:225]
	v_pk_fma_f32 v[60:61], v[64:65], v[20:21], v[226:227]
	global_store_dwordx4 v216, v[94:97], s[22:23]
	global_store_dwordx4 v216, v[74:77], s[22:23] offset:16
	v_pk_mul_f32 v[142:143], v[156:157], v[94:95]
	v_pk_mul_f32 v[144:145], v[158:159], v[96:97]
	v_pk_mul_f32 v[242:243], v[160:161], v[74:75]
	v_pk_mul_f32 v[244:245], v[162:163], v[76:77]
	v_cvt_pk_bf16_f32 v142, v142, v143
	v_cvt_pk_bf16_f32 v143, v144, v145
	v_cvt_pk_bf16_f32 v144, v242, v243
	v_cvt_pk_bf16_f32 v145, v244, v245
	global_store_dwordx4 v217, v[142:145], s[26:27]
	global_store_dwordx4 v216, v[78:81], s[22:23] offset:512
	global_store_dwordx4 v216, v[58:61], s[22:23] offset:528
	v_pk_mul_f32 v[212:213], v[164:165], v[78:79]
	v_pk_mul_f32 v[214:215], v[166:167], v[80:81]
	v_pk_mul_f32 v[242:243], v[168:169], v[58:59]
	v_pk_mul_f32 v[244:245], v[170:171], v[60:61]
	v_cvt_pk_bf16_f32 v212, v212, v213
	v_cvt_pk_bf16_f32 v213, v214, v215
	v_cvt_pk_bf16_f32 v214, v242, v243
	v_cvt_pk_bf16_f32 v215, v244, v245
	global_store_dwordx4 v217, v[212:215], s[26:27] offset:256
	s_add_u32 s22, s22, 0x10000
	s_addc_u32 s23, s23, 0
	s_add_u32 s26, s26, 0x8000
	s_addc_u32 s27, s27, 0
	s_waitcnt vmcnt(16)
	v_pk_fma_f32 v[62:63], v[42:43], v[30:31], v[172:173]
	v_pk_fma_f32 v[64:65], v[44:45], v[32:33], v[174:175]
	v_pk_fma_f32 v[42:43], v[46:47], v[26:27], v[176:177]
	v_pk_fma_f32 v[44:45], v[48:49], v[28:29], v[178:179]
	v_pk_fma_f32 v[46:47], v[34:35], v[22:23], v[180:181]
	v_pk_fma_f32 v[48:49], v[36:37], v[24:25], v[182:183]
	v_pk_fma_f32 v[34:35], v[38:39], v[18:19], v[184:185]
	v_pk_fma_f32 v[36:37], v[40:41], v[20:21], v[186:187]
	global_store_dwordx4 v216, v[62:65], s[22:23]
	global_store_dwordx4 v216, v[42:45], s[22:23] offset:16
	v_pk_mul_f32 v[142:143], v[156:157], v[62:63]
	v_pk_mul_f32 v[144:145], v[158:159], v[64:65]
	v_pk_mul_f32 v[172:173], v[160:161], v[42:43]
	v_pk_mul_f32 v[174:175], v[162:163], v[44:45]
	v_cvt_pk_bf16_f32 v142, v142, v143
	v_cvt_pk_bf16_f32 v143, v144, v145
	v_cvt_pk_bf16_f32 v144, v172, v173
	v_cvt_pk_bf16_f32 v145, v174, v175
	global_store_dwordx4 v217, v[142:145], s[26:27]
	global_store_dwordx4 v216, v[46:49], s[22:23] offset:512
	global_store_dwordx4 v216, v[34:37], s[22:23] offset:528
	v_pk_mul_f32 v[212:213], v[164:165], v[46:47]
	v_pk_mul_f32 v[214:215], v[166:167], v[48:49]
	v_pk_mul_f32 v[172:173], v[168:169], v[34:35]
	v_pk_mul_f32 v[174:175], v[170:171], v[36:37]
	v_cvt_pk_bf16_f32 v212, v212, v213
	v_cvt_pk_bf16_f32 v213, v214, v215
	v_cvt_pk_bf16_f32 v214, v172, v173
	v_cvt_pk_bf16_f32 v215, v174, v175
	global_store_dwordx4 v217, v[212:215], s[26:27] offset:256
	s_add_u32 s22, s22, 0x10000
	s_addc_u32 s23, s23, 0
	s_add_u32 s26, s26, 0x8000
	s_addc_u32 s27, s27, 0
	s_waitcnt vmcnt(12)
	v_pk_fma_f32 v[30:31], v[10:11], v[30:31], v[188:189]
	v_pk_fma_f32 v[32:33], v[12:13], v[32:33], v[190:191]
	v_pk_fma_f32 v[10:11], v[14:15], v[26:27], v[230:231]
	v_pk_fma_f32 v[12:13], v[16:17], v[28:29], v[232:233]
	v_pk_fma_f32 v[14:15], v[2:3], v[22:23], v[234:235]
	v_pk_fma_f32 v[16:17], v[4:5], v[24:25], v[236:237]
	v_pk_fma_f32 v[2:3], v[6:7], v[18:19], v[238:239]
	v_pk_fma_f32 v[4:5], v[8:9], v[20:21], v[240:241]
	global_store_dwordx4 v216, v[30:33], s[22:23]
	global_store_dwordx4 v216, v[10:13], s[22:23] offset:16
	v_pk_mul_f32 v[142:143], v[156:157], v[30:31]
	v_pk_mul_f32 v[144:145], v[158:159], v[32:33]
	v_pk_mul_f32 v[188:189], v[160:161], v[10:11]
	v_pk_mul_f32 v[190:191], v[162:163], v[12:13]
	v_cvt_pk_bf16_f32 v142, v142, v143
	v_cvt_pk_bf16_f32 v143, v144, v145
	v_cvt_pk_bf16_f32 v144, v188, v189
	v_cvt_pk_bf16_f32 v145, v190, v191
	global_store_dwordx4 v217, v[142:145], s[26:27]
	global_store_dwordx4 v216, v[14:17], s[22:23] offset:512
	global_store_dwordx4 v216, v[2:5], s[22:23] offset:528
	v_pk_mul_f32 v[212:213], v[164:165], v[14:15]
	v_pk_mul_f32 v[214:215], v[166:167], v[16:17]
	v_pk_mul_f32 v[188:189], v[168:169], v[2:3]
	v_pk_mul_f32 v[190:191], v[170:171], v[4:5]
	v_cvt_pk_bf16_f32 v212, v212, v213
	v_cvt_pk_bf16_f32 v213, v214, v215
	v_cvt_pk_bf16_f32 v214, v188, v189
	v_cvt_pk_bf16_f32 v215, v190, v191
	global_store_dwordx4 v217, v[212:215], s[26:27] offset:256
	v_lshlrev_b32_e32 v0, 2, v210
	v_cmp_gt_u32_e32 vcc, 16, v210
	v_lshlrev_b32_e32 v18, 10, v209
	v_lshlrev_b32_e32 v19, 4, v155
	v_xor_b32_e32 v6, 64, v0
	ds_bpermute_b32 v8, v6, v138
	v_xor_b32_e32 v0, 0x80, v0
	v_lshl_add_u32 v7, v211, 2, 16
	v_add3_u32 v7, v7, v18, v19
	s_waitcnt lgkmcnt(0)
	v_add_f32_e32 v8, v138, v8
	ds_bpermute_b32 v9, v0, v8
	s_and_saveexec_b64 s[20:21], vcc
	s_cbranch_execz .LBB0_657
	s_waitcnt lgkmcnt(0)
	v_add_f32_e32 v8, v8, v9
	ds_write_b32 v7, v8 offset:49152
